# S5 in-projection GEMM: unit order in two groups of four column tiles (2 MiB of weights per XCD round instead of 4)
# speedup vs baseline: 1.0008x; 1.0008x over previous
;     __device__ __forceinline__ bool next(int i, Unit& u) const {
;         const int L = i * G + (((i + 1) * G <= n) ? c : cp); if (L >= n) return false;
;         if (mode == 0) { u.pm = L / nN; u.pn = L - u.pm * nN; }
.LBB0_1421:
	s_cmp_lt_i32 s34, 15
	s_cselect_b64 s[6:7], -1, 0
	s_cmp_gt_i32 s35, 14
	s_cselect_b64 s[8:9], -1, 0
	s_and_b64 s[6:7], s[6:7], s[8:9]
	s_andn2_b64 vcc, exec, s[6:7]
	s_cbranch_vccnz .LBB0_1504
	s_lshl_b32 s3, s2, 5
	s_and_b32 s3, s3, 0xe0
	s_ashr_i32 s6, s2, 3
	s_add_i32 s3, s3, s6
	s_cmpk_eq_i32 s30, 0x100
	s_cselect_b32 s3, s3, s2
	s_cmpk_gt_i32 s30, 0x220
	s_cselect_b32 s7, s2, s3
	s_cmpk_gt_i32 s7, 0x21f
	s_cbranch_scc1 .Lp14o_a
	s_cmpk_gt_u32 s7, 0x10f
	s_cselect_b32 s94, 1, 0
	s_mul_i32 s95, s94, 0x110
	s_sub_i32 s95, s7, s95
	s_lshl_b32 s94, s94, 2
	s_lshr_b32 s7, s95, 2
	s_lshl_b32 s7, s7, 3
	s_and_b32 s95, s95, 3
	s_add_i32 s94, s94, s95
	s_add_i32 s7, s7, s94
.Lp14o_a:
	s_cmpk_lt_i32 s7, 0x220
	s_cselect_b64 s[8:9], -1, 0
	s_cmpk_gt_i32 s7, 0x21f
	v_readfirstlane_b32 s18, v128
	s_cbranch_scc1 .LBB0_1424
	s_ashr_i32 s6, s7, 31
	s_lshr_b32 s6, s6, 29
	s_add_i32 s6, s7, s6
	s_ashr_i32 s46, s6, 3
	s_and_b32 s6, s6, -8
	s_sub_i32 s6, s7, s6

;     __device__ __forceinline__ bool next(int i, Unit& u) const {
;         const int L = i * G + (((i + 1) * G <= n) ? c : cp); if (L >= n) return false;
;         if (mode == 0) { u.pm = L / nN; u.pn = L - u.pm * nN; }
.LBB0_1430:
	s_add_i32 s73, s73, 1
	s_mul_i32 s7, s73, s30
	s_add_i32 s8, s7, s30
	s_cmpk_gt_i32 s8, 0x220
	s_cselect_b32 s8, s2, s3
	s_add_i32 s7, s8, s7
	s_cmpk_gt_i32 s7, 0x21f
	s_cbranch_scc1 .Lp14o_b
	s_cmpk_gt_u32 s7, 0x10f
	s_cselect_b32 s94, 1, 0
	s_mul_i32 s95, s94, 0x110
	s_sub_i32 s95, s7, s95
	s_lshl_b32 s94, s94, 2
	s_lshr_b32 s7, s95, 2
	s_lshl_b32 s7, s7, 3
	s_and_b32 s95, s95, 3
	s_add_i32 s94, s94, s95
	s_add_i32 s7, s7, s94
.Lp14o_b:
	s_cmpk_lt_i32 s7, 0x220
	s_cselect_b64 s[42:43], -1, 0
	s_cmpk_gt_i32 s7, 0x21f
	s_cbranch_scc1 .LBB0_1432
	s_ashr_i32 s8, s7, 31
	s_lshr_b32 s8, s8, 29
	s_add_i32 s8, s7, s8
	s_ashr_i32 s20, s8, 3
	s_and_b32 s8, s8, -8
	s_sub_i32 s22, s7, s8
